# v36 + nt on the P4/P5 epilogue loads of the gate / merged tiles (read once)
# baseline (speedup 1.0000x reference)
; __device__ __forceinline__ float bf_lo(unsigned w) { return __uint_as_float(w << 16); }
; __device__ __forceinline__ float bf_hi(unsigned w) { return __uint_as_float(w & 0xffff0000u); }
; #define PG8_PACK8(v0, v1) ((u32x4){cvt_pk_bf16((v0)[0], (v0)[1]), cvt_pk_bf16((v0)[2], (v0)[3]), cvt_pk_bf16((v1)[0], (v1)[1]), cvt_pk_bf16((v1)[2], (v1)[3])})
;     __device__ __forceinline__ void operator()(const f32x4 (&acc)[2][2][4][2], const Unit& u, int wr, int wc, int fr, int fq) const {
;         const int row0 = u.pm * BM + wr * 64 + fr, col0 = u.pn * BM + wc * 32 + 8 * fq;
;         constexpr int MB = SECOND ? 2 : 4;
; #pragma unroll
;         for (int ai = 0; ai < 2; ++ai)
; #pragma unroll
;           for (int mb = 0; mb < 4; mb += MB) { u32x4 gq[MB][2], oq[MB][2];
; #pragma unroll
;             for (int m = 0; m < MB; ++m)
; #pragma unroll
;                 for (int bj = 0; bj < 2; ++bj) { const size_t row = (size_t)(row0 + ai * HALF + (mb + m) * 16); const int col = col0 + bj * HALF;
;                     gq[m][bj] = *(const u32x4*)(gate + row * 4096 + goff + col); if (SECOND) oq[m][bj] = *(const u32x4*)(merged + row * 2048 + col); }
;             asm volatile("" ::: "memory");
; #pragma unroll
;             for (int m = 0; m < MB; ++m)
; #pragma unroll
;                 for (int bj = 0; bj < 2; ++bj) { const size_t row = (size_t)(row0 + ai * HALF + (mb + m) * 16); const int col = col0 + bj * HALF; const u32x4 g = gq[m][bj];
;                     f32x4 v0 = acc[ai][bj][mb + m][0], v1 = acc[ai][bj][mb + m][1];
;                     v0[0] *= bf_lo(g.x); v0[1] *= bf_hi(g.x); v0[2] *= bf_lo(g.y); v0[3] *= bf_hi(g.y);
;                     v1[0] *= bf_lo(g.z); v1[1] *= bf_hi(g.z); v1[2] *= bf_lo(g.w); v1[3] *= bf_hi(g.w);
;                     if (SECOND) { const u32x4 o = oq[m][bj];
;                         v0[0] += bf_lo(o.x); v0[1] += bf_hi(o.x); v0[2] += bf_lo(o.y); v0[3] += bf_hi(o.y);
;                         v1[0] += bf_lo(o.z); v1[1] += bf_hi(o.z); v1[2] += bf_lo(o.w); v1[3] += bf_hi(o.w); }
;                     *(u32x4*)(merged + row * 2048 + col) = PG8_PACK8(v0, v1); }
;             asm volatile("" ::: "memory"); }
.LBB0_697:
	v_lshl_add_u32 v166, s55, 8, v174
	v_lshl_or_b32 v130, s54, 8, v176
	v_ashrrev_i32_e32 v167, 31, v166
	v_ashrrev_i32_e32 v131, 31, v130
	v_lshlrev_b64 v[132:133], 13, v[166:167]
	v_lshl_add_u64 v[132:133], s[12:13], 0, v[132:133]
	v_lshlrev_b64 v[164:165], 1, v[130:131]
	v_lshl_add_u64 v[130:131], v[132:133], 0, v[164:165]
	global_load_dwordx4 v[178:181], v[130:131], off nt
	global_load_dwordx4 v[182:185], v[130:131], off offset:256 nt
	v_or_b32_e32 v172, 16, v166
	v_ashrrev_i32_e32 v173, 31, v172
	v_lshlrev_b64 v[130:131], 13, v[172:173]
	v_lshl_add_u64 v[130:131], s[12:13], 0, v[130:131]
	v_lshl_add_u64 v[130:131], v[130:131], 0, v[164:165]
	global_load_dwordx4 v[150:153], v[130:131], off nt
	global_load_dwordx4 v[146:149], v[130:131], off offset:256 nt
	v_or_b32_e32 v170, 32, v166
	v_ashrrev_i32_e32 v171, 31, v170
	v_lshlrev_b64 v[130:131], 13, v[170:171]
	v_lshl_add_u64 v[130:131], s[12:13], 0, v[130:131]
	v_lshl_add_u64 v[130:131], v[130:131], 0, v[164:165]
	global_load_dwordx4 v[142:145], v[130:131], off nt
	global_load_dwordx4 v[134:137], v[130:131], off offset:256 nt
	v_or_b32_e32 v168, 48, v166
	v_ashrrev_i32_e32 v169, 31, v168
	v_lshlrev_b64 v[130:131], 13, v[168:169]
	v_lshl_add_u64 v[130:131], s[12:13], 0, v[130:131]
	v_lshl_add_u64 v[130:131], v[130:131], 0, v[164:165]
	global_load_dwordx4 v[138:141], v[130:131], off nt
	s_nop 0
	global_load_dwordx4 v[130:133], v[130:131], off offset:256 nt
	v_lshlrev_b64 v[186:187], 12, v[166:167]
	s_mov_b64 s[26:27], -1
	s_andn2_b64 vcc, exec, s[6:7]
	s_waitcnt vmcnt(0)
	v_lshlrev_b32_e32 v188, 16, v178
	v_and_b32_e32 v189, 0xffff0000, v178
	v_lshlrev_b32_e32 v178, 16, v179
	v_and_b32_e32 v179, 0xffff0000, v179
	v_pk_mul_f32 v[128:129], v[128:129], v[178:179]
	v_lshlrev_b32_e32 v178, 16, v180
	v_and_b32_e32 v179, 0xffff0000, v180
	v_pk_mul_f32 v[126:127], v[126:127], v[188:189]
	v_pk_mul_f32 v[178:179], v[122:123], v[178:179]
	v_lshlrev_b32_e32 v122, 16, v181
	v_and_b32_e32 v123, 0xffff0000, v181
	v_pk_mul_f32 v[180:181], v[124:125], v[122:123]
	v_cvt_pk_bf16_f32 v122, v126, v127
	v_lshl_add_u64 v[126:127], s[10:11], 0, v[186:187]
	v_cvt_pk_bf16_f32 v123, v128, v129
	v_cvt_pk_bf16_f32 v124, v178, v179
	v_cvt_pk_bf16_f32 v125, v180, v181
	v_lshl_add_u64 v[126:127], v[126:127], 0, v[164:165]
	global_store_dwordx4 v[126:127], v[122:125], off
	s_nop 1
	v_lshlrev_b32_e32 v122, 16, v182
	v_and_b32_e32 v123, 0xffff0000, v182
	v_pk_mul_f32 v[118:119], v[118:119], v[122:123]
	v_lshlrev_b32_e32 v122, 16, v183
	v_and_b32_e32 v123, 0xffff0000, v183
	v_pk_mul_f32 v[120:121], v[120:121], v[122:123]
	v_lshlrev_b32_e32 v122, 16, v184
	v_and_b32_e32 v123, 0xffff0000, v184
	v_pk_mul_f32 v[122:123], v[114:115], v[122:123]
	v_lshlrev_b32_e32 v114, 16, v185
	v_and_b32_e32 v115, 0xffff0000, v185
	v_pk_mul_f32 v[124:125], v[116:117], v[114:115]
	v_cvt_pk_bf16_f32 v114, v118, v119
	v_cvt_pk_bf16_f32 v115, v120, v121
	v_cvt_pk_bf16_f32 v116, v122, v123
	v_cvt_pk_bf16_f32 v117, v124, v125
	global_store_dwordx4 v[126:127], v[114:117], off offset:256
	s_nop 1
	v_lshlrev_b32_e32 v116, 16, v150
	v_and_b32_e32 v117, 0xffff0000, v150
	v_pk_mul_f32 v[110:111], v[110:111], v[116:117]
	v_lshlrev_b32_e32 v116, 16, v151
	v_and_b32_e32 v117, 0xffff0000, v151
	v_pk_mul_f32 v[112:113], v[112:113], v[116:117]
	v_lshlrev_b32_e32 v116, 16, v152
	v_and_b32_e32 v117, 0xffff0000, v152
	v_lshlrev_b64 v[114:115], 12, v[172:173]
	v_pk_mul_f32 v[106:107], v[106:107], v[116:117]
	v_lshlrev_b32_e32 v116, 16, v153
	v_and_b32_e32 v117, 0xffff0000, v153
	v_pk_mul_f32 v[116:117], v[108:109], v[116:117]
	v_cvt_pk_bf16_f32 v108, v110, v111
	v_cvt_pk_bf16_f32 v110, v106, v107
	v_lshl_add_u64 v[106:107], s[10:11], 0, v[114:115]
	v_cvt_pk_bf16_f32 v109, v112, v113
	v_cvt_pk_bf16_f32 v111, v116, v117
	v_lshl_add_u64 v[106:107], v[106:107], 0, v[164:165]
	global_store_dwordx4 v[106:107], v[108:111], off
	s_nop 1
	v_lshlrev_b32_e32 v108, 16, v146
	v_and_b32_e32 v109, 0xffff0000, v146
	v_pk_mul_f32 v[102:103], v[102:103], v[108:109]
	v_lshlrev_b32_e32 v108, 16, v147
	v_and_b32_e32 v109, 0xffff0000, v147
	v_pk_mul_f32 v[104:105], v[104:105], v[108:109]
	v_lshlrev_b32_e32 v108, 16, v148
	v_and_b32_e32 v109, 0xffff0000, v148
	v_pk_mul_f32 v[108:109], v[94:95], v[108:109]
	v_lshlrev_b32_e32 v94, 16, v149
	v_and_b32_e32 v95, 0xffff0000, v149
	v_pk_mul_f32 v[110:111], v[96:97], v[94:95]
	v_cvt_pk_bf16_f32 v94, v102, v103
	v_cvt_pk_bf16_f32 v95, v104, v105
	v_cvt_pk_bf16_f32 v96, v108, v109
	v_cvt_pk_bf16_f32 v97, v110, v111
	global_store_dwordx4 v[106:107], v[94:97], off offset:256
	v_add_u32_e32 v104, 0xb0, v166
	v_ashrrev_i32_e32 v105, 31, v104
	v_lshlrev_b32_e32 v96, 16, v142
	v_and_b32_e32 v97, 0xffff0000, v142
	v_pk_mul_f32 v[96:97], v[98:99], v[96:97]
	v_lshlrev_b32_e32 v98, 16, v143
	v_and_b32_e32 v99, 0xffff0000, v143
	v_pk_mul_f32 v[98:99], v[100:101], v[98:99]
	v_lshlrev_b32_e32 v100, 16, v144
	v_and_b32_e32 v101, 0xffff0000, v144
	v_lshlrev_b64 v[94:95], 12, v[170:171]
	v_pk_mul_f32 v[100:101], v[90:91], v[100:101]
	v_lshlrev_b32_e32 v90, 16, v145
	v_and_b32_e32 v91, 0xffff0000, v145
	v_pk_mul_f32 v[102:103], v[92:93], v[90:91]
	v_lshl_add_u64 v[94:95], s[10:11], 0, v[94:95]
	v_cvt_pk_bf16_f32 v90, v96, v97
	v_cvt_pk_bf16_f32 v91, v98, v99
	v_cvt_pk_bf16_f32 v92, v100, v101
	v_cvt_pk_bf16_f32 v93, v102, v103
	v_lshl_add_u64 v[94:95], v[94:95], 0, v[164:165]
	global_store_dwordx4 v[94:95], v[90:93], off
	v_add_u32_e32 v98, 0x80, v166
	v_ashrrev_i32_e32 v99, 31, v98
	v_lshlrev_b32_e32 v90, 16, v134
	v_and_b32_e32 v91, 0xffff0000, v134
	v_pk_mul_f32 v[86:87], v[86:87], v[90:91]
	v_lshlrev_b32_e32 v90, 16, v135
	v_and_b32_e32 v91, 0xffff0000, v135
; __device__ __forceinline__ float bf_lo(unsigned w) { return __uint_as_float(w << 16); }
; __device__ __forceinline__ float bf_hi(unsigned w) { return __uint_as_float(w & 0xffff0000u); }
; #define PG8_PACK8(v0, v1) ((u32x4){cvt_pk_bf16((v0)[0], (v0)[1]), cvt_pk_bf16((v0)[2], (v0)[3]), cvt_pk_bf16((v1)[0], (v1)[1]), cvt_pk_bf16((v1)[2], (v1)[3])})
;     __device__ __forceinline__ void operator()(const f32x4 (&acc)[2][2][4][2], const Unit& u, int wr, int wc, int fr, int fq) const {
;     ...
;           for (int mb = 0; mb < 4; mb += MB) { u32x4 gq[MB][2], oq[MB][2];
; #pragma unroll
;             for (int m = 0; m < MB; ++m)
; #pragma unroll
;                 for (int bj = 0; bj < 2; ++bj) { const size_t row = (size_t)(row0 + ai * HALF + (mb + m) * 16); const int col = col0 + bj * HALF;
;                     gq[m][bj] = *(const u32x4*)(gate + row * 4096 + goff + col); if (SECOND) oq[m][bj] = *(const u32x4*)(merged + row * 2048 + col); }
;             asm volatile("" ::: "memory");
; #pragma unroll
;             for (int m = 0; m < MB; ++m)
; #pragma unroll
;                 for (int bj = 0; bj < 2; ++bj) { const size_t row = (size_t)(row0 + ai * HALF + (mb + m) * 16); const int col = col0 + bj * HALF; const u32x4 g = gq[m][bj];
;                     f32x4 v0 = acc[ai][bj][mb + m][0], v1 = acc[ai][bj][mb + m][1];
;                     v0[0] *= bf_lo(g.x); v0[1] *= bf_hi(g.x); v0[2] *= bf_lo(g.y); v0[3] *= bf_hi(g.y);
;                     v1[0] *= bf_lo(g.z); v1[1] *= bf_hi(g.z); v1[2] *= bf_lo(g.w); v1[3] *= bf_hi(g.w);
;                     if (SECOND) { const u32x4 o = oq[m][bj];
;                         v0[0] += bf_lo(o.x); v0[1] += bf_hi(o.x); v0[2] += bf_lo(o.y); v0[3] += bf_hi(o.y);
;                         v1[0] += bf_lo(o.z); v1[1] += bf_hi(o.z); v1[2] += bf_lo(o.w); v1[3] += bf_hi(o.w); }
;                     *(u32x4*)(merged + row * 2048 + col) = PG8_PACK8(v0, v1); }
	v_pk_mul_f32 v[88:89], v[88:89], v[90:91]
	v_lshlrev_b32_e32 v90, 16, v136
	v_and_b32_e32 v91, 0xffff0000, v136
	v_pk_mul_f32 v[90:91], v[78:79], v[90:91]
	v_lshlrev_b32_e32 v78, 16, v137
	v_and_b32_e32 v79, 0xffff0000, v137
	v_pk_mul_f32 v[92:93], v[80:81], v[78:79]
	v_cvt_pk_bf16_f32 v78, v86, v87
	v_cvt_pk_bf16_f32 v79, v88, v89
	v_cvt_pk_bf16_f32 v80, v90, v91
	v_cvt_pk_bf16_f32 v81, v92, v93
	global_store_dwordx4 v[94:95], v[78:81], off offset:256
	v_add_u32_e32 v100, 0x90, v166
	v_ashrrev_i32_e32 v101, 31, v100
	v_lshlrev_b32_e32 v80, 16, v138
	v_and_b32_e32 v81, 0xffff0000, v138
	v_pk_mul_f32 v[80:81], v[82:83], v[80:81]
	v_lshlrev_b32_e32 v82, 16, v139
	v_and_b32_e32 v83, 0xffff0000, v139
	v_pk_mul_f32 v[82:83], v[84:85], v[82:83]
	v_lshlrev_b32_e32 v84, 16, v140
	v_and_b32_e32 v85, 0xffff0000, v140
	v_lshlrev_b64 v[78:79], 12, v[168:169]
	v_pk_mul_f32 v[84:85], v[74:75], v[84:85]
	v_lshlrev_b32_e32 v74, 16, v141
	v_and_b32_e32 v75, 0xffff0000, v141
	v_pk_mul_f32 v[86:87], v[76:77], v[74:75]
	v_lshl_add_u64 v[78:79], s[10:11], 0, v[78:79]
	v_cvt_pk_bf16_f32 v74, v80, v81
	v_cvt_pk_bf16_f32 v75, v82, v83
	v_cvt_pk_bf16_f32 v76, v84, v85
	v_cvt_pk_bf16_f32 v77, v86, v87
	v_lshl_add_u64 v[78:79], v[78:79], 0, v[164:165]
	global_store_dwordx4 v[78:79], v[74:77], off
	v_add_u32_e32 v102, 0xa0, v166
	v_ashrrev_i32_e32 v103, 31, v102
	v_lshlrev_b32_e32 v74, 16, v130
	v_and_b32_e32 v75, 0xffff0000, v130
	v_pk_mul_f32 v[70:71], v[70:71], v[74:75]
	v_lshlrev_b32_e32 v74, 16, v131
	v_and_b32_e32 v75, 0xffff0000, v131
	v_pk_mul_f32 v[72:73], v[72:73], v[74:75]
	v_lshlrev_b32_e32 v74, 16, v132
	v_and_b32_e32 v75, 0xffff0000, v132
	v_pk_mul_f32 v[74:75], v[66:67], v[74:75]
	v_lshlrev_b32_e32 v66, 16, v133
	v_and_b32_e32 v67, 0xffff0000, v133
	v_pk_mul_f32 v[76:77], v[68:69], v[66:67]
	v_cvt_pk_bf16_f32 v66, v70, v71
	v_cvt_pk_bf16_f32 v67, v72, v73
	v_cvt_pk_bf16_f32 v68, v74, v75
	v_cvt_pk_bf16_f32 v69, v76, v77
	global_store_dwordx4 v[78:79], v[66:69], off offset:256
	s_nop 1
	v_lshlrev_b64 v[66:67], 13, v[98:99]
	v_lshl_add_u64 v[66:67], s[12:13], 0, v[66:67]
	v_lshl_add_u64 v[66:67], v[66:67], 0, v[164:165]
	global_load_dwordx4 v[70:73], v[66:67], off nt
	global_load_dwordx4 v[74:77], v[66:67], off offset:256 nt
	v_lshlrev_b64 v[66:67], 13, v[100:101]
	v_lshl_add_u64 v[66:67], s[12:13], 0, v[66:67]
	v_lshl_add_u64 v[66:67], v[66:67], 0, v[164:165]
	global_load_dwordx4 v[78:81], v[66:67], off nt
	global_load_dwordx4 v[82:85], v[66:67], off offset:256 nt
	v_lshlrev_b64 v[66:67], 13, v[102:103]
	v_lshl_add_u64 v[66:67], s[12:13], 0, v[66:67]
	v_lshl_add_u64 v[66:67], v[66:67], 0, v[164:165]
	global_load_dwordx4 v[86:89], v[66:67], off nt
	global_load_dwordx4 v[90:93], v[66:67], off offset:256 nt
	v_lshlrev_b64 v[66:67], 13, v[104:105]
	v_lshl_add_u64 v[66:67], s[12:13], 0, v[66:67]
	v_lshl_add_u64 v[66:67], v[66:67], 0, v[164:165]
	global_load_dwordx4 v[94:97], v[66:67], off nt
	s_nop 0
	global_load_dwordx4 v[66:69], v[66:67], off offset:256 nt
	v_lshlrev_b64 v[98:99], 12, v[98:99]
	s_waitcnt vmcnt(7)
	v_lshlrev_b32_e32 v106, 16, v70
	v_and_b32_e32 v107, 0xffff0000, v70
	v_lshlrev_b32_e32 v70, 16, v71
	v_and_b32_e32 v71, 0xffff0000, v71
	v_pk_mul_f32 v[64:65], v[64:65], v[70:71]
	v_lshlrev_b32_e32 v70, 16, v72
	v_and_b32_e32 v71, 0xffff0000, v72
	v_pk_mul_f32 v[62:63], v[62:63], v[106:107]
	v_pk_mul_f32 v[70:71], v[58:59], v[70:71]
	v_lshlrev_b32_e32 v58, 16, v73
	v_and_b32_e32 v59, 0xffff0000, v73
	v_pk_mul_f32 v[72:73], v[60:61], v[58:59]
	v_cvt_pk_bf16_f32 v58, v62, v63
	v_lshl_add_u64 v[62:63], s[10:11], 0, v[98:99]
	v_cvt_pk_bf16_f32 v59, v64, v65
	v_cvt_pk_bf16_f32 v60, v70, v71
	v_cvt_pk_bf16_f32 v61, v72, v73
	v_lshl_add_u64 v[62:63], v[62:63], 0, v[164:165]
	global_store_dwordx4 v[62:63], v[58:61], off
	s_waitcnt vmcnt(7)
	s_nop 0
	v_lshlrev_b32_e32 v58, 16, v74
	v_and_b32_e32 v59, 0xffff0000, v74
	v_pk_mul_f32 v[54:55], v[54:55], v[58:59]
	v_lshlrev_b32_e32 v58, 16, v75
	v_and_b32_e32 v59, 0xffff0000, v75
	v_pk_mul_f32 v[56:57], v[56:57], v[58:59]
	v_lshlrev_b32_e32 v58, 16, v76
	v_and_b32_e32 v59, 0xffff0000, v76
	v_pk_mul_f32 v[58:59], v[46:47], v[58:59]
	v_lshlrev_b32_e32 v46, 16, v77
	v_and_b32_e32 v47, 0xffff0000, v77
	v_pk_mul_f32 v[60:61], v[48:49], v[46:47]
	v_cvt_pk_bf16_f32 v46, v54, v55
	v_cvt_pk_bf16_f32 v47, v56, v57
	v_cvt_pk_bf16_f32 v48, v58, v59
	v_cvt_pk_bf16_f32 v49, v60, v61
	global_store_dwordx4 v[62:63], v[46:49], off offset:256
	s_waitcnt vmcnt(7)
; __device__ __forceinline__ float bf_lo(unsigned w) { return __uint_as_float(w << 16); }
; __device__ __forceinline__ float bf_hi(unsigned w) { return __uint_as_float(w & 0xffff0000u); }
; #define PG8_PACK8(v0, v1) ((u32x4){cvt_pk_bf16((v0)[0], (v0)[1]), cvt_pk_bf16((v0)[2], (v0)[3]), cvt_pk_bf16((v1)[0], (v1)[1]), cvt_pk_bf16((v1)[2], (v1)[3])})
;     __device__ __forceinline__ void operator()(const f32x4 (&acc)[2][2][4][2], const Unit& u, int wr, int wc, int fr, int fq) const {
;     ...
; #pragma unroll
;             for (int m = 0; m < MB; ++m)
; #pragma unroll
;                 for (int bj = 0; bj < 2; ++bj) { const size_t row = (size_t)(row0 + ai * HALF + (mb + m) * 16); const int col = col0 + bj * HALF; const u32x4 g = gq[m][bj];
;                     f32x4 v0 = acc[ai][bj][mb + m][0], v1 = acc[ai][bj][mb + m][1];
;                     v0[0] *= bf_lo(g.x); v0[1] *= bf_hi(g.x); v0[2] *= bf_lo(g.y); v0[3] *= bf_hi(g.y);
;                     v1[0] *= bf_lo(g.z); v1[1] *= bf_hi(g.z); v1[2] *= bf_lo(g.w); v1[3] *= bf_hi(g.w);
;                     if (SECOND) { const u32x4 o = oq[m][bj];
;                         v0[0] += bf_lo(o.x); v0[1] += bf_hi(o.x); v0[2] += bf_lo(o.y); v0[3] += bf_hi(o.y);
;                         v1[0] += bf_lo(o.z); v1[1] += bf_hi(o.z); v1[2] += bf_lo(o.w); v1[3] += bf_hi(o.w); }
;                     *(u32x4*)(merged + row * 2048 + col) = PG8_PACK8(v0, v1); }
;             asm volatile("" ::: "memory"); }
	s_nop 0
	v_lshlrev_b32_e32 v48, 16, v78
	v_and_b32_e32 v49, 0xffff0000, v78
	v_pk_mul_f32 v[48:49], v[50:51], v[48:49]
	v_lshlrev_b32_e32 v50, 16, v79
	v_and_b32_e32 v51, 0xffff0000, v79
	v_pk_mul_f32 v[50:51], v[52:53], v[50:51]
	v_lshlrev_b32_e32 v52, 16, v80
	v_and_b32_e32 v53, 0xffff0000, v80
	v_lshlrev_b64 v[46:47], 12, v[100:101]
	v_pk_mul_f32 v[52:53], v[42:43], v[52:53]
	v_lshlrev_b32_e32 v42, 16, v81
	v_and_b32_e32 v43, 0xffff0000, v81
	v_pk_mul_f32 v[54:55], v[44:45], v[42:43]
	v_lshl_add_u64 v[46:47], s[10:11], 0, v[46:47]
	v_cvt_pk_bf16_f32 v42, v48, v49
	v_cvt_pk_bf16_f32 v43, v50, v51
	v_cvt_pk_bf16_f32 v44, v52, v53
	v_cvt_pk_bf16_f32 v45, v54, v55
	v_lshl_add_u64 v[46:47], v[46:47], 0, v[164:165]
	global_store_dwordx4 v[46:47], v[42:45], off
	s_waitcnt vmcnt(7)
	s_nop 0
	v_lshlrev_b32_e32 v42, 16, v82
	v_and_b32_e32 v43, 0xffff0000, v82
	v_pk_mul_f32 v[38:39], v[38:39], v[42:43]
	v_lshlrev_b32_e32 v42, 16, v83
	v_and_b32_e32 v43, 0xffff0000, v83
	v_pk_mul_f32 v[40:41], v[40:41], v[42:43]
	v_lshlrev_b32_e32 v42, 16, v84
	v_and_b32_e32 v43, 0xffff0000, v84
	v_pk_mul_f32 v[42:43], v[30:31], v[42:43]
	v_lshlrev_b32_e32 v30, 16, v85
	v_and_b32_e32 v31, 0xffff0000, v85
	v_pk_mul_f32 v[44:45], v[32:33], v[30:31]
	v_cvt_pk_bf16_f32 v30, v38, v39
	v_cvt_pk_bf16_f32 v31, v40, v41
	v_cvt_pk_bf16_f32 v32, v42, v43
	v_cvt_pk_bf16_f32 v33, v44, v45
	global_store_dwordx4 v[46:47], v[30:33], off offset:256
	s_waitcnt vmcnt(7)
	s_nop 0
	v_lshlrev_b32_e32 v32, 16, v86
	v_and_b32_e32 v33, 0xffff0000, v86
	v_pk_mul_f32 v[32:33], v[34:35], v[32:33]
	v_lshlrev_b32_e32 v34, 16, v87
	v_and_b32_e32 v35, 0xffff0000, v87
	v_pk_mul_f32 v[34:35], v[36:37], v[34:35]
	v_lshlrev_b32_e32 v36, 16, v88
	v_and_b32_e32 v37, 0xffff0000, v88
	v_lshlrev_b64 v[30:31], 12, v[102:103]
	v_pk_mul_f32 v[36:37], v[26:27], v[36:37]
	v_lshlrev_b32_e32 v26, 16, v89
	v_and_b32_e32 v27, 0xffff0000, v89
	v_pk_mul_f32 v[38:39], v[28:29], v[26:27]
	v_lshl_add_u64 v[30:31], s[10:11], 0, v[30:31]
	v_cvt_pk_bf16_f32 v26, v32, v33
	v_cvt_pk_bf16_f32 v27, v34, v35
	v_cvt_pk_bf16_f32 v28, v36, v37
	v_cvt_pk_bf16_f32 v29, v38, v39
	v_lshl_add_u64 v[30:31], v[30:31], 0, v[164:165]
	global_store_dwordx4 v[30:31], v[26:29], off
	s_waitcnt vmcnt(7)
	s_nop 0
	v_lshlrev_b32_e32 v26, 16, v90
	v_and_b32_e32 v27, 0xffff0000, v90
	v_pk_mul_f32 v[22:23], v[22:23], v[26:27]
	v_lshlrev_b32_e32 v26, 16, v91
	v_and_b32_e32 v27, 0xffff0000, v91
	v_pk_mul_f32 v[24:25], v[24:25], v[26:27]
	v_lshlrev_b32_e32 v26, 16, v92
	v_and_b32_e32 v27, 0xffff0000, v92
	v_pk_mul_f32 v[26:27], v[14:15], v[26:27]
	v_lshlrev_b32_e32 v14, 16, v93
	v_and_b32_e32 v15, 0xffff0000, v93
	v_pk_mul_f32 v[28:29], v[16:17], v[14:15]
	v_cvt_pk_bf16_f32 v14, v22, v23
	v_cvt_pk_bf16_f32 v15, v24, v25
	v_cvt_pk_bf16_f32 v16, v26, v27
	v_cvt_pk_bf16_f32 v17, v28, v29
	global_store_dwordx4 v[30:31], v[14:17], off offset:256
	s_waitcnt vmcnt(7)
	s_nop 0
	v_lshlrev_b32_e32 v16, 16, v94
	v_and_b32_e32 v17, 0xffff0000, v94
	v_pk_mul_f32 v[16:17], v[18:19], v[16:17]
	v_lshlrev_b32_e32 v18, 16, v95
	v_and_b32_e32 v19, 0xffff0000, v95
	v_pk_mul_f32 v[18:19], v[20:21], v[18:19]
	v_lshlrev_b32_e32 v20, 16, v96
	v_and_b32_e32 v21, 0xffff0000, v96
	v_lshlrev_b64 v[14:15], 12, v[104:105]
	v_pk_mul_f32 v[20:21], v[10:11], v[20:21]
	v_lshlrev_b32_e32 v10, 16, v97
	v_and_b32_e32 v11, 0xffff0000, v97
	v_pk_mul_f32 v[22:23], v[12:13], v[10:11]
	v_lshl_add_u64 v[14:15], s[10:11], 0, v[14:15]
	v_cvt_pk_bf16_f32 v10, v16, v17
	v_cvt_pk_bf16_f32 v11, v18, v19
	v_cvt_pk_bf16_f32 v12, v20, v21
	v_cvt_pk_bf16_f32 v13, v22, v23
	v_lshl_add_u64 v[14:15], v[14:15], 0, v[164:165]
	global_store_dwordx4 v[14:15], v[10:13], off
	s_waitcnt vmcnt(7)
	s_nop 0
	v_lshlrev_b32_e32 v10, 16, v66
	v_and_b32_e32 v11, 0xffff0000, v66
	v_pk_mul_f32 v[6:7], v[6:7], v[10:11]
	v_lshlrev_b32_e32 v10, 16, v67
	v_and_b32_e32 v11, 0xffff0000, v67
	v_pk_mul_f32 v[8:9], v[8:9], v[10:11]
	v_lshlrev_b32_e32 v10, 16, v68
	v_and_b32_e32 v11, 0xffff0000, v68
	v_pk_mul_f32 v[10:11], v[2:3], v[10:11]
	v_lshlrev_b32_e32 v2, 16, v69
	v_and_b32_e32 v3, 0xffff0000, v69
	v_pk_mul_f32 v[12:13], v[4:5], v[2:3]
	v_cvt_pk_bf16_f32 v2, v6, v7
	v_cvt_pk_bf16_f32 v3, v8, v9
	v_cvt_pk_bf16_f32 v4, v10, v11
	v_cvt_pk_bf16_f32 v5, v12, v13
	global_store_dwordx4 v[14:15], v[2:5], off offset:256
	s_cbranch_vccnz .LBB0_686
	s_andn2_b64 vcc, exec, s[14:15]
	s_cbranch_vccnz .LBB0_685
	s_barrier
	s_branch .LBB0_685

; __device__ __forceinline__ float bf_lo(unsigned w) { return __uint_as_float(w << 16); }
; __device__ __forceinline__ float bf_hi(unsigned w) { return __uint_as_float(w & 0xffff0000u); }
; #define PG8_PACK8(v0, v1) ((u32x4){cvt_pk_bf16((v0)[0], (v0)[1]), cvt_pk_bf16((v0)[2], (v0)[3]), cvt_pk_bf16((v1)[0], (v1)[1]), cvt_pk_bf16((v1)[2], (v1)[3])})
;     __device__ __forceinline__ void operator()(const f32x4 (&acc)[2][2][4][2], const Unit& u, int wr, int wc, int fr, int fq) const {
;         const int row0 = u.pm * BM + wr * 64 + fr, col0 = u.pn * BM + wc * 32 + 8 * fq;
;         constexpr int MB = SECOND ? 2 : 4;
; #pragma unroll
;         for (int ai = 0; ai < 2; ++ai)
; #pragma unroll
;           for (int mb = 0; mb < 4; mb += MB) { u32x4 gq[MB][2], oq[MB][2];
; #pragma unroll
;             for (int m = 0; m < MB; ++m)
; #pragma unroll
;                 for (int bj = 0; bj < 2; ++bj) { const size_t row = (size_t)(row0 + ai * HALF + (mb + m) * 16); const int col = col0 + bj * HALF;
;                     gq[m][bj] = *(const u32x4*)(gate + row * 4096 + goff + col); if (SECOND) oq[m][bj] = *(const u32x4*)(merged + row * 2048 + col); }
;             asm volatile("" ::: "memory");
; #pragma unroll
;             for (int m = 0; m < MB; ++m)
; #pragma unroll
;                 for (int bj = 0; bj < 2; ++bj) { const size_t row = (size_t)(row0 + ai * HALF + (mb + m) * 16); const int col = col0 + bj * HALF; const u32x4 g = gq[m][bj];
;                     f32x4 v0 = acc[ai][bj][mb + m][0], v1 = acc[ai][bj][mb + m][1];
;                     v0[0] *= bf_lo(g.x); v0[1] *= bf_hi(g.x); v0[2] *= bf_lo(g.y); v0[3] *= bf_hi(g.y);
;                     v1[0] *= bf_lo(g.z); v1[1] *= bf_hi(g.z); v1[2] *= bf_lo(g.w); v1[3] *= bf_hi(g.w);
;                     if (SECOND) { const u32x4 o = oq[m][bj];
;                         v0[0] += bf_lo(o.x); v0[1] += bf_hi(o.x); v0[2] += bf_lo(o.y); v0[3] += bf_hi(o.y);
;                         v1[0] += bf_lo(o.z); v1[1] += bf_hi(o.z); v1[2] += bf_lo(o.w); v1[3] += bf_hi(o.w); }
;                     *(u32x4*)(merged + row * 2048 + col) = PG8_PACK8(v0, v1); }
.LBB0_761:
	v_lshl_add_u32 v156, s55, 8, v162
	v_lshl_or_b32 v130, s54, 8, v164
	v_ashrrev_i32_e32 v157, 31, v156
	v_ashrrev_i32_e32 v131, 31, v130
	v_lshlrev_b64 v[132:133], 13, v[156:157]
	v_lshl_add_u64 v[132:133], s[16:17], 0, v[132:133]
	v_lshlrev_b64 v[158:159], 1, v[130:131]
	v_lshlrev_b64 v[134:135], 12, v[156:157]
	v_lshl_add_u64 v[130:131], v[132:133], 0, v[158:159]
	v_lshl_add_u64 v[134:135], s[10:11], 0, v[134:135]
	global_load_dwordx4 v[166:169], v[130:131], off nt
	v_lshl_add_u64 v[182:183], v[134:135], 0, v[158:159]
	global_load_dwordx4 v[170:173], v[182:183], off nt
	global_load_dwordx4 v[174:177], v[130:131], off offset:256 nt
	global_load_dwordx4 v[178:181], v[182:183], off offset:256 nt
	v_or_b32_e32 v130, 16, v156
	v_ashrrev_i32_e32 v131, 31, v130
	v_lshlrev_b64 v[132:133], 13, v[130:131]
	v_lshl_add_u64 v[132:133], s[16:17], 0, v[132:133]
	v_lshlrev_b64 v[130:131], 12, v[130:131]
	v_lshl_add_u64 v[132:133], v[132:133], 0, v[158:159]
	v_lshl_add_u64 v[130:131], s[10:11], 0, v[130:131]
	global_load_dwordx4 v[142:145], v[132:133], off nt
	v_lshl_add_u64 v[160:161], v[130:131], 0, v[158:159]
	global_load_dwordx4 v[138:141], v[160:161], off nt
	global_load_dwordx4 v[134:137], v[132:133], off offset:256 nt
	s_nop 0
	global_load_dwordx4 v[130:133], v[160:161], off offset:256 nt
	s_mov_b64 s[26:27], -1
	s_andn2_b64 vcc, exec, s[6:7]
	s_waitcnt vmcnt(0)
	v_lshlrev_b32_e32 v186, 16, v170
	v_lshlrev_b32_e32 v184, 16, v166
	v_and_b32_e32 v185, 0xffff0000, v166
	v_and_b32_e32 v187, 0xffff0000, v170
	v_lshlrev_b32_e32 v166, 16, v167
	v_and_b32_e32 v167, 0xffff0000, v167
	v_lshlrev_b32_e32 v170, 16, v171
	v_and_b32_e32 v171, 0xffff0000, v171
	v_pk_fma_f32 v[128:129], v[128:129], v[166:167], v[170:171]
	v_lshlrev_b32_e32 v166, 16, v168
	v_and_b32_e32 v167, 0xffff0000, v168
	v_lshlrev_b32_e32 v170, 16, v172
	v_and_b32_e32 v171, 0xffff0000, v172
	v_pk_fma_f32 v[166:167], v[122:123], v[166:167], v[170:171]
	v_lshlrev_b32_e32 v122, 16, v169
	v_and_b32_e32 v123, 0xffff0000, v169
	v_lshlrev_b32_e32 v168, 16, v173
	v_and_b32_e32 v169, 0xffff0000, v173
	v_pk_fma_f32 v[126:127], v[126:127], v[184:185], v[186:187]
	v_pk_fma_f32 v[168:169], v[124:125], v[122:123], v[168:169]
	v_cvt_pk_bf16_f32 v122, v126, v127
	v_cvt_pk_bf16_f32 v123, v128, v129
	v_cvt_pk_bf16_f32 v124, v166, v167
	v_cvt_pk_bf16_f32 v125, v168, v169
	global_store_dwordx4 v[182:183], v[122:125], off
	s_nop 1
	v_lshlrev_b32_e32 v122, 16, v174
	v_and_b32_e32 v123, 0xffff0000, v174
	v_lshlrev_b32_e32 v124, 16, v178
	v_and_b32_e32 v125, 0xffff0000, v178
	v_pk_fma_f32 v[118:119], v[118:119], v[122:123], v[124:125]
	v_lshlrev_b32_e32 v122, 16, v175
	v_and_b32_e32 v123, 0xffff0000, v175
	v_lshlrev_b32_e32 v124, 16, v179
	v_and_b32_e32 v125, 0xffff0000, v179
	v_pk_fma_f32 v[120:121], v[120:121], v[122:123], v[124:125]
	v_lshlrev_b32_e32 v122, 16, v176
	v_and_b32_e32 v123, 0xffff0000, v176
	v_lshlrev_b32_e32 v124, 16, v180
	v_and_b32_e32 v125, 0xffff0000, v180
	v_pk_fma_f32 v[122:123], v[114:115], v[122:123], v[124:125]
	v_lshlrev_b32_e32 v114, 16, v177
	v_and_b32_e32 v115, 0xffff0000, v177
	v_lshlrev_b32_e32 v124, 16, v181
	v_and_b32_e32 v125, 0xffff0000, v181
	v_pk_fma_f32 v[124:125], v[116:117], v[114:115], v[124:125]
	v_cvt_pk_bf16_f32 v114, v118, v119
	v_cvt_pk_bf16_f32 v115, v120, v121
	v_cvt_pk_bf16_f32 v116, v122, v123
	v_cvt_pk_bf16_f32 v117, v124, v125
	global_store_dwordx4 v[182:183], v[114:117], off offset:256
	s_nop 1
	v_lshlrev_b32_e32 v114, 16, v142
	v_and_b32_e32 v115, 0xffff0000, v142
	v_lshlrev_b32_e32 v116, 16, v138
	v_and_b32_e32 v117, 0xffff0000, v138
	v_pk_fma_f32 v[110:111], v[110:111], v[114:115], v[116:117]
	v_lshlrev_b32_e32 v114, 16, v143
	v_and_b32_e32 v115, 0xffff0000, v143
	v_lshlrev_b32_e32 v116, 16, v139
	v_and_b32_e32 v117, 0xffff0000, v139
	v_pk_fma_f32 v[112:113], v[112:113], v[114:115], v[116:117]
	v_lshlrev_b32_e32 v114, 16, v144
	v_and_b32_e32 v115, 0xffff0000, v144
	v_lshlrev_b32_e32 v116, 16, v140
	v_and_b32_e32 v117, 0xffff0000, v140
	v_pk_fma_f32 v[114:115], v[106:107], v[114:115], v[116:117]
	v_lshlrev_b32_e32 v106, 16, v145
	v_and_b32_e32 v107, 0xffff0000, v145
	v_lshlrev_b32_e32 v116, 16, v141
	v_and_b32_e32 v117, 0xffff0000, v141
	v_pk_fma_f32 v[116:117], v[108:109], v[106:107], v[116:117]
	v_cvt_pk_bf16_f32 v106, v110, v111
	v_cvt_pk_bf16_f32 v107, v112, v113
	v_cvt_pk_bf16_f32 v108, v114, v115
	v_cvt_pk_bf16_f32 v109, v116, v117
	global_store_dwordx4 v[160:161], v[106:109], off
	v_or_b32_e32 v114, 48, v156
	v_ashrrev_i32_e32 v115, 31, v114
	v_lshlrev_b32_e32 v106, 16, v134
	v_and_b32_e32 v107, 0xffff0000, v134
	v_lshlrev_b32_e32 v108, 16, v130
	v_and_b32_e32 v109, 0xffff0000, v130
	v_pk_fma_f32 v[102:103], v[102:103], v[106:107], v[108:109]
	v_lshlrev_b32_e32 v106, 16, v135
	v_and_b32_e32 v107, 0xffff0000, v135
	v_lshlrev_b32_e32 v108, 16, v131
	v_and_b32_e32 v109, 0xffff0000, v131
	v_pk_fma_f32 v[104:105], v[104:105], v[106:107], v[108:109]
	v_lshlrev_b32_e32 v106, 16, v136
	v_and_b32_e32 v107, 0xffff0000, v136
	v_lshlrev_b32_e32 v108, 16, v132
	v_and_b32_e32 v109, 0xffff0000, v132
	v_pk_fma_f32 v[106:107], v[98:99], v[106:107], v[108:109]
	v_lshlrev_b32_e32 v98, 16, v137
	v_and_b32_e32 v99, 0xffff0000, v137
	v_lshlrev_b32_e32 v108, 16, v133
	v_and_b32_e32 v109, 0xffff0000, v133
	v_pk_fma_f32 v[108:109], v[100:101], v[98:99], v[108:109]
	v_cvt_pk_bf16_f32 v98, v102, v103
	v_cvt_pk_bf16_f32 v99, v104, v105
	v_cvt_pk_bf16_f32 v100, v106, v107
	v_cvt_pk_bf16_f32 v101, v108, v109
	global_store_dwordx4 v[160:161], v[98:101], off offset:256
	v_lshlrev_b64 v[116:117], 13, v[114:115]
	v_lshl_add_u64 v[116:117], s[16:17], 0, v[116:117]
	v_or_b32_e32 v98, 32, v156
	v_ashrrev_i32_e32 v99, 31, v98
	v_lshlrev_b64 v[100:101], 13, v[98:99]
	v_lshl_add_u64 v[100:101], s[16:17], 0, v[100:101]
	v_lshlrev_b64 v[98:99], 12, v[98:99]
	v_lshl_add_u64 v[106:107], v[100:101], 0, v[158:159]
	v_lshl_add_u64 v[102:103], s[10:11], 0, v[98:99]
	global_load_dwordx4 v[98:101], v[106:107], off nt
	v_lshl_add_u64 v[130:131], v[102:103], 0, v[158:159]
	global_load_dwordx4 v[102:105], v[130:131], off nt
	s_nop 0
	global_load_dwordx4 v[106:109], v[106:107], off offset:256 nt
	s_nop 0
	global_load_dwordx4 v[110:113], v[130:131], off offset:256 nt
	v_lshlrev_b64 v[114:115], 12, v[114:115]
	v_lshl_add_u64 v[122:123], v[116:117], 0, v[158:159]
	v_lshl_add_u64 v[118:119], s[10:11], 0, v[114:115]
	global_load_dwordx4 v[114:117], v[122:123], off nt
	v_lshl_add_u64 v[132:133], v[118:119], 0, v[158:159]
	global_load_dwordx4 v[118:121], v[132:133], off nt
	s_nop 0
	global_load_dwordx4 v[122:125], v[122:123], off offset:256 nt
	s_nop 0
	global_load_dwordx4 v[126:129], v[132:133], off offset:256 nt
	s_waitcnt vmcnt(7)
; __device__ __forceinline__ float bf_lo(unsigned w) { return __uint_as_float(w << 16); }
; __device__ __forceinline__ float bf_hi(unsigned w) { return __uint_as_float(w & 0xffff0000u); }
; #define PG8_PACK8(v0, v1) ((u32x4){cvt_pk_bf16((v0)[0], (v0)[1]), cvt_pk_bf16((v0)[2], (v0)[3]), cvt_pk_bf16((v1)[0], (v1)[1]), cvt_pk_bf16((v1)[2], (v1)[3])})
;     __device__ __forceinline__ void operator()(const f32x4 (&acc)[2][2][4][2], const Unit& u, int wr, int wc, int fr, int fq) const {
;     ...
;           for (int mb = 0; mb < 4; mb += MB) { u32x4 gq[MB][2], oq[MB][2];
; #pragma unroll
;             for (int m = 0; m < MB; ++m)
; #pragma unroll
;                 for (int bj = 0; bj < 2; ++bj) { const size_t row = (size_t)(row0 + ai * HALF + (mb + m) * 16); const int col = col0 + bj * HALF;
;                     gq[m][bj] = *(const u32x4*)(gate + row * 4096 + goff + col); if (SECOND) oq[m][bj] = *(const u32x4*)(merged + row * 2048 + col); }
;             asm volatile("" ::: "memory");
; #pragma unroll
;             for (int m = 0; m < MB; ++m)
; #pragma unroll
;                 for (int bj = 0; bj < 2; ++bj) { const size_t row = (size_t)(row0 + ai * HALF + (mb + m) * 16); const int col = col0 + bj * HALF; const u32x4 g = gq[m][bj];
;                     f32x4 v0 = acc[ai][bj][mb + m][0], v1 = acc[ai][bj][mb + m][1];
;                     v0[0] *= bf_lo(g.x); v0[1] *= bf_hi(g.x); v0[2] *= bf_lo(g.y); v0[3] *= bf_hi(g.y);
;                     v1[0] *= bf_lo(g.z); v1[1] *= bf_hi(g.z); v1[2] *= bf_lo(g.w); v1[3] *= bf_hi(g.w);
;                     if (SECOND) { const u32x4 o = oq[m][bj];
;                         v0[0] += bf_lo(o.x); v0[1] += bf_hi(o.x); v0[2] += bf_lo(o.y); v0[3] += bf_hi(o.y);
;                         v1[0] += bf_lo(o.z); v1[1] += bf_hi(o.z); v1[2] += bf_lo(o.w); v1[3] += bf_hi(o.w); }
;                     *(u32x4*)(merged + row * 2048 + col) = PG8_PACK8(v0, v1); }
	v_lshlrev_b32_e32 v134, 16, v98
	v_and_b32_e32 v135, 0xffff0000, v98
	s_waitcnt vmcnt(6)
	v_lshlrev_b32_e32 v136, 16, v102
	v_and_b32_e32 v137, 0xffff0000, v102
	v_lshlrev_b32_e32 v98, 16, v99
	v_and_b32_e32 v99, 0xffff0000, v99
	v_lshlrev_b32_e32 v102, 16, v103
	v_and_b32_e32 v103, 0xffff0000, v103
	v_pk_fma_f32 v[96:97], v[96:97], v[98:99], v[102:103]
	v_lshlrev_b32_e32 v98, 16, v100
	v_and_b32_e32 v99, 0xffff0000, v100
	v_lshlrev_b32_e32 v102, 16, v104
	v_and_b32_e32 v103, 0xffff0000, v104
	v_pk_fma_f32 v[98:99], v[90:91], v[98:99], v[102:103]
	v_lshlrev_b32_e32 v90, 16, v101
	v_and_b32_e32 v91, 0xffff0000, v101
	v_lshlrev_b32_e32 v100, 16, v105
	v_and_b32_e32 v101, 0xffff0000, v105
	v_pk_fma_f32 v[94:95], v[94:95], v[134:135], v[136:137]
	v_pk_fma_f32 v[100:101], v[92:93], v[90:91], v[100:101]
	v_cvt_pk_bf16_f32 v90, v94, v95
	v_cvt_pk_bf16_f32 v91, v96, v97
	v_cvt_pk_bf16_f32 v92, v98, v99
	v_cvt_pk_bf16_f32 v93, v100, v101
	global_store_dwordx4 v[130:131], v[90:93], off
	s_waitcnt vmcnt(6)
	s_nop 0
	v_lshlrev_b32_e32 v90, 16, v106
	v_and_b32_e32 v91, 0xffff0000, v106
	s_waitcnt vmcnt(5)
	v_lshlrev_b32_e32 v92, 16, v110
	v_and_b32_e32 v93, 0xffff0000, v110
	v_pk_fma_f32 v[86:87], v[86:87], v[90:91], v[92:93]
	v_lshlrev_b32_e32 v90, 16, v107
	v_and_b32_e32 v91, 0xffff0000, v107
	v_lshlrev_b32_e32 v92, 16, v111
	v_and_b32_e32 v93, 0xffff0000, v111
	v_pk_fma_f32 v[88:89], v[88:89], v[90:91], v[92:93]
	v_lshlrev_b32_e32 v90, 16, v108
	v_and_b32_e32 v91, 0xffff0000, v108
	v_lshlrev_b32_e32 v92, 16, v112
	v_and_b32_e32 v93, 0xffff0000, v112
	v_pk_fma_f32 v[90:91], v[82:83], v[90:91], v[92:93]
	v_lshlrev_b32_e32 v82, 16, v109
	v_and_b32_e32 v83, 0xffff0000, v109
	v_lshlrev_b32_e32 v92, 16, v113
	v_and_b32_e32 v93, 0xffff0000, v113
	v_pk_fma_f32 v[92:93], v[84:85], v[82:83], v[92:93]
	v_cvt_pk_bf16_f32 v82, v86, v87
	v_cvt_pk_bf16_f32 v83, v88, v89
	v_cvt_pk_bf16_f32 v84, v90, v91
	v_cvt_pk_bf16_f32 v85, v92, v93
	global_store_dwordx4 v[130:131], v[82:85], off offset:256
	s_waitcnt vmcnt(5)
	s_nop 0
	v_lshlrev_b32_e32 v82, 16, v114
	v_and_b32_e32 v83, 0xffff0000, v114
	s_waitcnt vmcnt(4)
	v_lshlrev_b32_e32 v84, 16, v118
	v_and_b32_e32 v85, 0xffff0000, v118
	v_pk_fma_f32 v[78:79], v[78:79], v[82:83], v[84:85]
	v_lshlrev_b32_e32 v82, 16, v115
	v_and_b32_e32 v83, 0xffff0000, v115
	v_lshlrev_b32_e32 v84, 16, v119
	v_and_b32_e32 v85, 0xffff0000, v119
	v_pk_fma_f32 v[80:81], v[80:81], v[82:83], v[84:85]
	v_lshlrev_b32_e32 v82, 16, v116
	v_and_b32_e32 v83, 0xffff0000, v116
	v_lshlrev_b32_e32 v84, 16, v120
	v_and_b32_e32 v85, 0xffff0000, v120
	v_pk_fma_f32 v[82:83], v[74:75], v[82:83], v[84:85]
	v_lshlrev_b32_e32 v74, 16, v117
	v_and_b32_e32 v75, 0xffff0000, v117
	v_lshlrev_b32_e32 v84, 16, v121
	v_and_b32_e32 v85, 0xffff0000, v121
	v_pk_fma_f32 v[84:85], v[76:77], v[74:75], v[84:85]
	v_cvt_pk_bf16_f32 v74, v78, v79
	v_cvt_pk_bf16_f32 v75, v80, v81
	v_cvt_pk_bf16_f32 v76, v82, v83
	v_cvt_pk_bf16_f32 v77, v84, v85
	global_store_dwordx4 v[132:133], v[74:77], off
	v_add_u32_e32 v82, 0x90, v156
	v_ashrrev_i32_e32 v83, 31, v82
	s_waitcnt vmcnt(4)
	v_lshlrev_b32_e32 v74, 16, v122
	v_and_b32_e32 v75, 0xffff0000, v122
	s_waitcnt vmcnt(3)
	v_lshlrev_b32_e32 v76, 16, v126
	v_and_b32_e32 v77, 0xffff0000, v126
	v_pk_fma_f32 v[70:71], v[70:71], v[74:75], v[76:77]
	v_lshlrev_b32_e32 v74, 16, v123
	v_and_b32_e32 v75, 0xffff0000, v123
	v_lshlrev_b32_e32 v76, 16, v127
	v_and_b32_e32 v77, 0xffff0000, v127
	v_pk_fma_f32 v[72:73], v[72:73], v[74:75], v[76:77]
	v_lshlrev_b32_e32 v74, 16, v124
	v_and_b32_e32 v75, 0xffff0000, v124
	v_lshlrev_b32_e32 v76, 16, v128
	v_and_b32_e32 v77, 0xffff0000, v128
	v_pk_fma_f32 v[74:75], v[66:67], v[74:75], v[76:77]
	v_lshlrev_b32_e32 v66, 16, v125
	v_and_b32_e32 v67, 0xffff0000, v125
	v_lshlrev_b32_e32 v76, 16, v129
	v_and_b32_e32 v77, 0xffff0000, v129
	v_pk_fma_f32 v[76:77], v[68:69], v[66:67], v[76:77]
	v_cvt_pk_bf16_f32 v66, v70, v71
	v_cvt_pk_bf16_f32 v67, v72, v73
	v_cvt_pk_bf16_f32 v68, v74, v75
	v_cvt_pk_bf16_f32 v69, v76, v77
	global_store_dwordx4 v[132:133], v[66:69], off offset:256
	v_lshlrev_b64 v[84:85], 13, v[82:83]
	v_lshl_add_u64 v[84:85], s[16:17], 0, v[84:85]
	v_add_u32_e32 v66, 0x80, v156
	v_ashrrev_i32_e32 v67, 31, v66
	v_lshlrev_b64 v[68:69], 13, v[66:67]
	v_lshl_add_u64 v[68:69], s[16:17], 0, v[68:69]
	v_lshlrev_b64 v[66:67], 12, v[66:67]
	v_lshl_add_u64 v[74:75], v[68:69], 0, v[158:159]
	v_lshl_add_u64 v[70:71], s[10:11], 0, v[66:67]
	global_load_dwordx4 v[66:69], v[74:75], off nt
	v_lshl_add_u64 v[98:99], v[70:71], 0, v[158:159]
	global_load_dwordx4 v[70:73], v[98:99], off nt
	s_nop 0
	global_load_dwordx4 v[74:77], v[74:75], off offset:256 nt
	s_nop 0
	global_load_dwordx4 v[78:81], v[98:99], off offset:256 nt
	v_lshlrev_b64 v[82:83], 12, v[82:83]
	v_lshl_add_u64 v[90:91], v[84:85], 0, v[158:159]
	v_lshl_add_u64 v[86:87], s[10:11], 0, v[82:83]
	global_load_dwordx4 v[82:85], v[90:91], off nt
	v_lshl_add_u64 v[100:101], v[86:87], 0, v[158:159]
	global_load_dwordx4 v[86:89], v[100:101], off nt
	s_nop 0
	global_load_dwordx4 v[90:93], v[90:91], off offset:256 nt
	s_nop 0
	global_load_dwordx4 v[94:97], v[100:101], off offset:256 nt
	s_waitcnt vmcnt(7)
	v_lshlrev_b32_e32 v102, 16, v66
	v_and_b32_e32 v103, 0xffff0000, v66
	s_waitcnt vmcnt(6)
; __device__ __forceinline__ float bf_lo(unsigned w) { return __uint_as_float(w << 16); }
; __device__ __forceinline__ float bf_hi(unsigned w) { return __uint_as_float(w & 0xffff0000u); }
; #define PG8_PACK8(v0, v1) ((u32x4){cvt_pk_bf16((v0)[0], (v0)[1]), cvt_pk_bf16((v0)[2], (v0)[3]), cvt_pk_bf16((v1)[0], (v1)[1]), cvt_pk_bf16((v1)[2], (v1)[3])})
;     __device__ __forceinline__ void operator()(const f32x4 (&acc)[2][2][4][2], const Unit& u, int wr, int wc, int fr, int fq) const {
;     ...
;           for (int mb = 0; mb < 4; mb += MB) { u32x4 gq[MB][2], oq[MB][2];
; #pragma unroll
;             for (int m = 0; m < MB; ++m)
; #pragma unroll
;                 for (int bj = 0; bj < 2; ++bj) { const size_t row = (size_t)(row0 + ai * HALF + (mb + m) * 16); const int col = col0 + bj * HALF;
;                     gq[m][bj] = *(const u32x4*)(gate + row * 4096 + goff + col); if (SECOND) oq[m][bj] = *(const u32x4*)(merged + row * 2048 + col); }
;             asm volatile("" ::: "memory");
; #pragma unroll
;             for (int m = 0; m < MB; ++m)
; #pragma unroll
;                 for (int bj = 0; bj < 2; ++bj) { const size_t row = (size_t)(row0 + ai * HALF + (mb + m) * 16); const int col = col0 + bj * HALF; const u32x4 g = gq[m][bj];
;                     f32x4 v0 = acc[ai][bj][mb + m][0], v1 = acc[ai][bj][mb + m][1];
;                     v0[0] *= bf_lo(g.x); v0[1] *= bf_hi(g.x); v0[2] *= bf_lo(g.y); v0[3] *= bf_hi(g.y);
;                     v1[0] *= bf_lo(g.z); v1[1] *= bf_hi(g.z); v1[2] *= bf_lo(g.w); v1[3] *= bf_hi(g.w);
;                     if (SECOND) { const u32x4 o = oq[m][bj];
;                         v0[0] += bf_lo(o.x); v0[1] += bf_hi(o.x); v0[2] += bf_lo(o.y); v0[3] += bf_hi(o.y);
;                         v1[0] += bf_lo(o.z); v1[1] += bf_hi(o.z); v1[2] += bf_lo(o.w); v1[3] += bf_hi(o.w); }
;                     *(u32x4*)(merged + row * 2048 + col) = PG8_PACK8(v0, v1); }
	v_lshlrev_b32_e32 v104, 16, v70
	v_and_b32_e32 v105, 0xffff0000, v70
	v_lshlrev_b32_e32 v66, 16, v67
	v_and_b32_e32 v67, 0xffff0000, v67
	v_lshlrev_b32_e32 v70, 16, v71
	v_and_b32_e32 v71, 0xffff0000, v71
	v_pk_fma_f32 v[64:65], v[64:65], v[66:67], v[70:71]
	v_lshlrev_b32_e32 v66, 16, v68
	v_and_b32_e32 v67, 0xffff0000, v68
	v_lshlrev_b32_e32 v70, 16, v72
	v_and_b32_e32 v71, 0xffff0000, v72
	v_pk_fma_f32 v[66:67], v[58:59], v[66:67], v[70:71]
	v_lshlrev_b32_e32 v58, 16, v69
	v_and_b32_e32 v59, 0xffff0000, v69
	v_lshlrev_b32_e32 v68, 16, v73
	v_and_b32_e32 v69, 0xffff0000, v73
	v_pk_fma_f32 v[62:63], v[62:63], v[102:103], v[104:105]
	v_pk_fma_f32 v[68:69], v[60:61], v[58:59], v[68:69]
	v_cvt_pk_bf16_f32 v58, v62, v63
	v_cvt_pk_bf16_f32 v59, v64, v65
	v_cvt_pk_bf16_f32 v60, v66, v67
	v_cvt_pk_bf16_f32 v61, v68, v69
	global_store_dwordx4 v[98:99], v[58:61], off
	s_waitcnt vmcnt(6)
	s_nop 0
	v_lshlrev_b32_e32 v58, 16, v74
	v_and_b32_e32 v59, 0xffff0000, v74
	s_waitcnt vmcnt(5)
	v_lshlrev_b32_e32 v60, 16, v78
	v_and_b32_e32 v61, 0xffff0000, v78
	v_pk_fma_f32 v[54:55], v[54:55], v[58:59], v[60:61]
	v_lshlrev_b32_e32 v58, 16, v75
	v_and_b32_e32 v59, 0xffff0000, v75
	v_lshlrev_b32_e32 v60, 16, v79
	v_and_b32_e32 v61, 0xffff0000, v79
	v_pk_fma_f32 v[56:57], v[56:57], v[58:59], v[60:61]
	v_lshlrev_b32_e32 v58, 16, v76
	v_and_b32_e32 v59, 0xffff0000, v76
	v_lshlrev_b32_e32 v60, 16, v80
	v_and_b32_e32 v61, 0xffff0000, v80
	v_pk_fma_f32 v[58:59], v[50:51], v[58:59], v[60:61]
	v_lshlrev_b32_e32 v50, 16, v77
	v_and_b32_e32 v51, 0xffff0000, v77
	v_lshlrev_b32_e32 v60, 16, v81
	v_and_b32_e32 v61, 0xffff0000, v81
	v_pk_fma_f32 v[60:61], v[52:53], v[50:51], v[60:61]
	v_cvt_pk_bf16_f32 v50, v54, v55
	v_cvt_pk_bf16_f32 v51, v56, v57
	v_cvt_pk_bf16_f32 v52, v58, v59
	v_cvt_pk_bf16_f32 v53, v60, v61
	global_store_dwordx4 v[98:99], v[50:53], off offset:256
	s_waitcnt vmcnt(5)
	s_nop 0
	v_lshlrev_b32_e32 v50, 16, v82
	v_and_b32_e32 v51, 0xffff0000, v82
	s_waitcnt vmcnt(4)
	v_lshlrev_b32_e32 v52, 16, v86
	v_and_b32_e32 v53, 0xffff0000, v86
	v_pk_fma_f32 v[46:47], v[46:47], v[50:51], v[52:53]
	v_lshlrev_b32_e32 v50, 16, v83
	v_and_b32_e32 v51, 0xffff0000, v83
	v_lshlrev_b32_e32 v52, 16, v87
	v_and_b32_e32 v53, 0xffff0000, v87
	v_pk_fma_f32 v[48:49], v[48:49], v[50:51], v[52:53]
	v_lshlrev_b32_e32 v50, 16, v84
	v_and_b32_e32 v51, 0xffff0000, v84
	v_lshlrev_b32_e32 v52, 16, v88
	v_and_b32_e32 v53, 0xffff0000, v88
	v_pk_fma_f32 v[50:51], v[42:43], v[50:51], v[52:53]
	v_lshlrev_b32_e32 v42, 16, v85
	v_and_b32_e32 v43, 0xffff0000, v85
	v_lshlrev_b32_e32 v52, 16, v89
	v_and_b32_e32 v53, 0xffff0000, v89
	v_pk_fma_f32 v[52:53], v[44:45], v[42:43], v[52:53]
	v_cvt_pk_bf16_f32 v42, v46, v47
	v_cvt_pk_bf16_f32 v43, v48, v49
	v_cvt_pk_bf16_f32 v44, v50, v51
	v_cvt_pk_bf16_f32 v45, v52, v53
	global_store_dwordx4 v[100:101], v[42:45], off
	v_add_u32_e32 v50, 0xb0, v156
	v_ashrrev_i32_e32 v51, 31, v50
	s_waitcnt vmcnt(4)
	v_lshlrev_b32_e32 v42, 16, v90
	v_and_b32_e32 v43, 0xffff0000, v90
	s_waitcnt vmcnt(3)
	v_lshlrev_b32_e32 v44, 16, v94
	v_and_b32_e32 v45, 0xffff0000, v94
	v_pk_fma_f32 v[38:39], v[38:39], v[42:43], v[44:45]
	v_lshlrev_b32_e32 v42, 16, v91
	v_and_b32_e32 v43, 0xffff0000, v91
	v_lshlrev_b32_e32 v44, 16, v95
	v_and_b32_e32 v45, 0xffff0000, v95
	v_pk_fma_f32 v[40:41], v[40:41], v[42:43], v[44:45]
	v_lshlrev_b32_e32 v42, 16, v92
	v_and_b32_e32 v43, 0xffff0000, v92
	v_lshlrev_b32_e32 v44, 16, v96
	v_and_b32_e32 v45, 0xffff0000, v96
	v_pk_fma_f32 v[42:43], v[34:35], v[42:43], v[44:45]
	v_lshlrev_b32_e32 v34, 16, v93
	v_and_b32_e32 v35, 0xffff0000, v93
	v_lshlrev_b32_e32 v44, 16, v97
	v_and_b32_e32 v45, 0xffff0000, v97
	v_pk_fma_f32 v[44:45], v[36:37], v[34:35], v[44:45]
	v_cvt_pk_bf16_f32 v34, v38, v39
	v_cvt_pk_bf16_f32 v35, v40, v41
	v_cvt_pk_bf16_f32 v36, v42, v43
	v_cvt_pk_bf16_f32 v37, v44, v45
	global_store_dwordx4 v[100:101], v[34:37], off offset:256
	v_lshlrev_b64 v[52:53], 13, v[50:51]
	v_lshl_add_u64 v[52:53], s[16:17], 0, v[52:53]
	v_add_u32_e32 v34, 0xa0, v156
	v_ashrrev_i32_e32 v35, 31, v34
	v_lshlrev_b64 v[36:37], 13, v[34:35]
	v_lshl_add_u64 v[36:37], s[16:17], 0, v[36:37]
	v_lshlrev_b64 v[34:35], 12, v[34:35]
	v_lshl_add_u64 v[42:43], v[36:37], 0, v[158:159]
	v_lshl_add_u64 v[38:39], s[10:11], 0, v[34:35]
	global_load_dwordx4 v[34:37], v[42:43], off nt
	v_lshl_add_u64 v[66:67], v[38:39], 0, v[158:159]
	global_load_dwordx4 v[38:41], v[66:67], off nt
	s_nop 0
	global_load_dwordx4 v[42:45], v[42:43], off offset:256 nt
	s_nop 0
	global_load_dwordx4 v[46:49], v[66:67], off offset:256 nt
	v_lshlrev_b64 v[50:51], 12, v[50:51]
	v_lshl_add_u64 v[58:59], v[52:53], 0, v[158:159]
	v_lshl_add_u64 v[54:55], s[10:11], 0, v[50:51]
	global_load_dwordx4 v[50:53], v[58:59], off nt
	v_lshl_add_u64 v[68:69], v[54:55], 0, v[158:159]
	global_load_dwordx4 v[54:57], v[68:69], off nt
	s_nop 0
	global_load_dwordx4 v[58:61], v[58:59], off offset:256 nt
	s_nop 0
	global_load_dwordx4 v[62:65], v[68:69], off offset:256 nt
	s_waitcnt vmcnt(7)
; __device__ __forceinline__ float bf_lo(unsigned w) { return __uint_as_float(w << 16); }
; __device__ __forceinline__ float bf_hi(unsigned w) { return __uint_as_float(w & 0xffff0000u); }
; #define PG8_PACK8(v0, v1) ((u32x4){cvt_pk_bf16((v0)[0], (v0)[1]), cvt_pk_bf16((v0)[2], (v0)[3]), cvt_pk_bf16((v1)[0], (v1)[1]), cvt_pk_bf16((v1)[2], (v1)[3])})
;     __device__ __forceinline__ void operator()(const f32x4 (&acc)[2][2][4][2], const Unit& u, int wr, int wc, int fr, int fq) const {
;     ...
; #pragma unroll
;             for (int m = 0; m < MB; ++m)
; #pragma unroll
;                 for (int bj = 0; bj < 2; ++bj) { const size_t row = (size_t)(row0 + ai * HALF + (mb + m) * 16); const int col = col0 + bj * HALF; const u32x4 g = gq[m][bj];
;                     f32x4 v0 = acc[ai][bj][mb + m][0], v1 = acc[ai][bj][mb + m][1];
;                     v0[0] *= bf_lo(g.x); v0[1] *= bf_hi(g.x); v0[2] *= bf_lo(g.y); v0[3] *= bf_hi(g.y);
;                     v1[0] *= bf_lo(g.z); v1[1] *= bf_hi(g.z); v1[2] *= bf_lo(g.w); v1[3] *= bf_hi(g.w);
;                     if (SECOND) { const u32x4 o = oq[m][bj];
;                         v0[0] += bf_lo(o.x); v0[1] += bf_hi(o.x); v0[2] += bf_lo(o.y); v0[3] += bf_hi(o.y);
;                         v1[0] += bf_lo(o.z); v1[1] += bf_hi(o.z); v1[2] += bf_lo(o.w); v1[3] += bf_hi(o.w); }
;                     *(u32x4*)(merged + row * 2048 + col) = PG8_PACK8(v0, v1); }
;             asm volatile("" ::: "memory"); }
	v_lshlrev_b32_e32 v70, 16, v34
	v_and_b32_e32 v71, 0xffff0000, v34
	s_waitcnt vmcnt(6)
	v_lshlrev_b32_e32 v72, 16, v38
	v_and_b32_e32 v73, 0xffff0000, v38
	v_lshlrev_b32_e32 v34, 16, v35
	v_and_b32_e32 v35, 0xffff0000, v35
	v_lshlrev_b32_e32 v38, 16, v39
	v_and_b32_e32 v39, 0xffff0000, v39
	v_pk_fma_f32 v[32:33], v[32:33], v[34:35], v[38:39]
	v_lshlrev_b32_e32 v34, 16, v36
	v_and_b32_e32 v35, 0xffff0000, v36
	v_lshlrev_b32_e32 v38, 16, v40
	v_and_b32_e32 v39, 0xffff0000, v40
	v_pk_fma_f32 v[34:35], v[26:27], v[34:35], v[38:39]
	v_lshlrev_b32_e32 v26, 16, v37
	v_and_b32_e32 v27, 0xffff0000, v37
	v_lshlrev_b32_e32 v36, 16, v41
	v_and_b32_e32 v37, 0xffff0000, v41
	v_pk_fma_f32 v[30:31], v[30:31], v[70:71], v[72:73]
	v_pk_fma_f32 v[36:37], v[28:29], v[26:27], v[36:37]
	v_cvt_pk_bf16_f32 v26, v30, v31
	v_cvt_pk_bf16_f32 v27, v32, v33
	v_cvt_pk_bf16_f32 v28, v34, v35
	v_cvt_pk_bf16_f32 v29, v36, v37
	global_store_dwordx4 v[66:67], v[26:29], off
	s_waitcnt vmcnt(6)
	s_nop 0
	v_lshlrev_b32_e32 v26, 16, v42
	v_and_b32_e32 v27, 0xffff0000, v42
	s_waitcnt vmcnt(5)
	v_lshlrev_b32_e32 v28, 16, v46
	v_and_b32_e32 v29, 0xffff0000, v46
	v_pk_fma_f32 v[22:23], v[22:23], v[26:27], v[28:29]
	v_lshlrev_b32_e32 v26, 16, v43
	v_and_b32_e32 v27, 0xffff0000, v43
	v_lshlrev_b32_e32 v28, 16, v47
	v_and_b32_e32 v29, 0xffff0000, v47
	v_pk_fma_f32 v[24:25], v[24:25], v[26:27], v[28:29]
	v_lshlrev_b32_e32 v26, 16, v44
	v_and_b32_e32 v27, 0xffff0000, v44
	v_lshlrev_b32_e32 v28, 16, v48
	v_and_b32_e32 v29, 0xffff0000, v48
	v_pk_fma_f32 v[26:27], v[18:19], v[26:27], v[28:29]
	v_lshlrev_b32_e32 v18, 16, v45
	v_and_b32_e32 v19, 0xffff0000, v45
	v_lshlrev_b32_e32 v28, 16, v49
	v_and_b32_e32 v29, 0xffff0000, v49
	v_pk_fma_f32 v[28:29], v[20:21], v[18:19], v[28:29]
	v_cvt_pk_bf16_f32 v18, v22, v23
	v_cvt_pk_bf16_f32 v19, v24, v25
	v_cvt_pk_bf16_f32 v20, v26, v27
	v_cvt_pk_bf16_f32 v21, v28, v29
	global_store_dwordx4 v[66:67], v[18:21], off offset:256
	s_waitcnt vmcnt(5)
	s_nop 0
	v_lshlrev_b32_e32 v18, 16, v50
	v_and_b32_e32 v19, 0xffff0000, v50
	s_waitcnt vmcnt(4)
	v_lshlrev_b32_e32 v20, 16, v54
	v_and_b32_e32 v21, 0xffff0000, v54
	v_pk_fma_f32 v[14:15], v[14:15], v[18:19], v[20:21]
	v_lshlrev_b32_e32 v18, 16, v51
	v_and_b32_e32 v19, 0xffff0000, v51
	v_lshlrev_b32_e32 v20, 16, v55
	v_and_b32_e32 v21, 0xffff0000, v55
	v_pk_fma_f32 v[16:17], v[16:17], v[18:19], v[20:21]
	v_lshlrev_b32_e32 v18, 16, v52
	v_and_b32_e32 v19, 0xffff0000, v52
	v_lshlrev_b32_e32 v20, 16, v56
	v_and_b32_e32 v21, 0xffff0000, v56
	v_pk_fma_f32 v[18:19], v[10:11], v[18:19], v[20:21]
	v_lshlrev_b32_e32 v10, 16, v53
	v_and_b32_e32 v11, 0xffff0000, v53
	v_lshlrev_b32_e32 v20, 16, v57
	v_and_b32_e32 v21, 0xffff0000, v57
	v_pk_fma_f32 v[20:21], v[12:13], v[10:11], v[20:21]
	v_cvt_pk_bf16_f32 v10, v14, v15
	v_cvt_pk_bf16_f32 v11, v16, v17
	v_cvt_pk_bf16_f32 v12, v18, v19
	v_cvt_pk_bf16_f32 v13, v20, v21
	global_store_dwordx4 v[68:69], v[10:13], off
	s_waitcnt vmcnt(4)
	s_nop 0
	v_lshlrev_b32_e32 v10, 16, v58
	v_and_b32_e32 v11, 0xffff0000, v58
	s_waitcnt vmcnt(3)
	v_lshlrev_b32_e32 v12, 16, v62
	v_and_b32_e32 v13, 0xffff0000, v62
	v_pk_fma_f32 v[6:7], v[6:7], v[10:11], v[12:13]
	v_lshlrev_b32_e32 v10, 16, v59
	v_and_b32_e32 v11, 0xffff0000, v59
	v_lshlrev_b32_e32 v12, 16, v63
	v_and_b32_e32 v13, 0xffff0000, v63
	v_pk_fma_f32 v[8:9], v[8:9], v[10:11], v[12:13]
	v_lshlrev_b32_e32 v10, 16, v60
	v_and_b32_e32 v11, 0xffff0000, v60
	v_lshlrev_b32_e32 v12, 16, v64
	v_and_b32_e32 v13, 0xffff0000, v64
	v_pk_fma_f32 v[10:11], v[2:3], v[10:11], v[12:13]
	v_lshlrev_b32_e32 v2, 16, v61
	v_and_b32_e32 v3, 0xffff0000, v61
	v_lshlrev_b32_e32 v12, 16, v65
	v_and_b32_e32 v13, 0xffff0000, v65
	v_pk_fma_f32 v[12:13], v[4:5], v[2:3], v[12:13]
	v_cvt_pk_bf16_f32 v2, v6, v7
	v_cvt_pk_bf16_f32 v3, v8, v9
	v_cvt_pk_bf16_f32 v4, v10, v11
	v_cvt_pk_bf16_f32 v5, v12, v13
	global_store_dwordx4 v[68:69], v[2:5], off offset:256
	s_cbranch_vccnz .LBB0_750
	s_andn2_b64 vcc, exec, s[12:13]
	s_cbranch_vccnz .LBB0_749
	s_barrier
	s_branch .LBB0_749
